# attention loop: removed recomputed canonicalizing v_max pairs and 0+x add on the serial rowmax-to-branch chain (on top of K swizzle + counted PV waits)
# speedup vs baseline: 1.0083x; 1.0083x over previous
; #define SBAR() __builtin_amdgcn_sched_barrier(0)
; #define QKT(P0, P1, KP) do { if constexpr (PRE) qkt<ND0>(P0, P1, KP, qr, r32, hi, negm); else qkt<ND0>(P0, P1, KP, qr, r32, hi); } while (0)
; #define PSM(P0, P1, MN, AL, FIRST) do { if constexpr (PRE) partialSM2(P0, P1, m_reg, negm, AL, thr2, FIRST); else partialSM(P0, P1, m_reg, MN, AL, C, thr_raw); } while (0)
; DEVFI void finishSM(f32x16& p0, f32x16& p1, float alpha, float& l_reg, bf16x8& pa0, bf16x8& pa1, bf16x8& pa2, bf16x8& pa3) {
; #pragma unroll
;     for (int r = 0; r < 16; ++r) p1[r] = __builtin_amdgcn_exp2f(p1[r]);
;     float ps = 0;
; #pragma unroll
;     for (int r = 0; r < 16; ++r) ps += p0[r];
; #pragma unroll
;     for (int r = 0; r < 16; ++r) ps += p1[r];
;     { auto rr = __builtin_amdgcn_permlane32_swap(__float_as_uint(ps), __float_as_uint(ps), false, false);
;       ps = __uint_as_float(rr[0]) + __uint_as_float(rr[1]); }
;     l_reg = l_reg * alpha + ps;
;     ...
;     PK4(p0, 0, pa0); PK4(p0, 8, pa1); PK4(p1, 0, pa2); PK4(p1, 8, pa3);
; template <int DQK, int DV, bool PRE = false>
; DEVFI void attn_unit(const bf16_t* __restrict__ Qb, int ldq, const bf16_t* __restrict__ Kh, int ldk, const bf16_t* __restrict__ Vh, int ldv,
;                      bf16_t* __restrict__ Ob, int ldo, int seq, float scale, char* lds) {
;     ...
;         SBAR(); QKT(pB0, pB1, K_lds + SHM_K);
;         finishSM(pA0, pA1, alA, l_reg, pa0, pa1, pa2, pa3); SBAR();
;         SLOAD(1, (j + 2) * KVBLK); SBAR();
;         pv_all<NCB>(o, vb0, pa0, pa1, pa2, pa3); PSM(pB0, pB1, mnB, alB, false);
.LBB0_1151:
	ds_read_b128 v[0:3], v177 offset:32768
	ds_read_b128 v[4:7], v177 offset:40960
	v_add_f32_e32 v8, v203, v205
	v_add_f32_e32 v8, v189, v8
	s_waitcnt lgkmcnt(1)
	v_mfma_f32_32x32x16_bf16 v[94:109], v[0:3], v[130:133], v[46:61]
	v_add_f32_e32 v8, v204, v8
	v_add_f32_e32 v8, v187, v8
	v_add_f32_e32 v8, v202, v8
	v_add_f32_e32 v8, v186, v8
	v_add_f32_e32 v8, v188, v8
	v_add_f32_e32 v8, v183, v8
	v_add_f32_e32 v8, v185, v8
	s_waitcnt lgkmcnt(0)
	v_mfma_f32_32x32x16_bf16 v[78:93], v[4:7], v[130:133], v[46:61]
	ds_read_b128 v[0:3], v178 offset:32768
	ds_read_b128 v[4:7], v178 offset:40960
	v_add_f32_e32 v8, v163, v8
	v_add_f32_e32 v8, v184, v8
	v_add_f32_e32 v8, v161, v8
	v_add_f32_e32 v8, v182, v8
	v_add_f32_e32 v8, v160, v8
	v_add_f32_e32 v8, v162, v8
	s_waitcnt lgkmcnt(1)
	v_mfma_f32_32x32x16_bf16 v[94:109], v[0:3], v[126:129], v[94:109]
	v_exp_f32_e32 v70, v70
	v_exp_f32_e32 v71, v71
	v_exp_f32_e32 v72, v72
	v_exp_f32_e32 v73, v73
	v_exp_f32_e32 v74, v74
	v_exp_f32_e32 v75, v75
	v_exp_f32_e32 v76, v76
	s_waitcnt lgkmcnt(0)
	v_mfma_f32_32x32x16_bf16 v[78:93], v[4:7], v[126:129], v[78:93]
	ds_read_b128 v[0:3], v176 offset:32768
	ds_read_b128 v[4:7], v176 offset:40960
	v_exp_f32_e32 v77, v77
	s_waitcnt lgkmcnt(1)
	v_mfma_f32_32x32x16_bf16 v[94:109], v[0:3], v[122:125], v[94:109]
	s_waitcnt lgkmcnt(0)
	v_mfma_f32_32x32x16_bf16 v[78:93], v[4:7], v[122:125], v[78:93]
	ds_read_b128 v[0:3], v175 offset:32768
	ds_read_b128 v[4:7], v175 offset:40960
	s_waitcnt lgkmcnt(1)
	v_mfma_f32_32x32x16_bf16 v[94:109], v[0:3], v[118:121], v[94:109]
	s_waitcnt lgkmcnt(0)
	v_mfma_f32_32x32x16_bf16 v[78:93], v[4:7], v[118:121], v[78:93]
	ds_read_b128 v[0:3], v174 offset:32768
	ds_read_b128 v[4:7], v174 offset:40960
	s_waitcnt lgkmcnt(1)
	v_mfma_f32_32x32x16_bf16 v[94:109], v[0:3], v[114:117], v[94:109]
	s_waitcnt lgkmcnt(0)
	v_mfma_f32_32x32x16_bf16 v[78:93], v[4:7], v[114:117], v[78:93]
	ds_read_b128 v[0:3], v172 offset:32768
	ds_read_b128 v[4:7], v172 offset:40960
	s_waitcnt lgkmcnt(1)
	v_mfma_f32_32x32x16_bf16 v[94:109], v[0:3], v[110:113], v[94:109]
	v_exp_f32_e32 v0, v62
	v_exp_f32_e32 v1, v63
	v_exp_f32_e32 v2, v64
	v_exp_f32_e32 v3, v65
	v_add_f32_e32 v8, v0, v8
	v_add_f32_e32 v8, v1, v8
	v_add_f32_e32 v8, v2, v8
	s_waitcnt lgkmcnt(0)
	v_mfma_f32_32x32x16_bf16 v[78:93], v[4:7], v[110:113], v[78:93]
	v_exp_f32_e32 v4, v66
	v_exp_f32_e32 v5, v67
	v_exp_f32_e32 v6, v68
	v_exp_f32_e32 v7, v69
	v_add_f32_e32 v8, v3, v8
	v_add_f32_e32 v8, v4, v8
	v_add_f32_e32 v8, v5, v8
	v_add_f32_e32 v8, v6, v8
	v_add_f32_e32 v8, v7, v8
	v_add_f32_e32 v8, v70, v8
	v_add_f32_e32 v8, v71, v8
	v_add_f32_e32 v8, v72, v8
	v_add_f32_e32 v8, v73, v8
	v_add_f32_e32 v8, v74, v8
	v_add_f32_e32 v8, v75, v8
	v_add_f32_e32 v8, v76, v8
	v_add_f32_e32 v13, v77, v8
	v_mov_b32_e32 v180, v13
	v_cvt_pk_bf16_f32 v8, v203, v205
	v_cvt_pk_bf16_f32 v9, v189, v204
	v_cvt_pk_bf16_f32 v10, v187, v202
	v_cvt_pk_bf16_f32 v11, v186, v188
	v_cvt_pk_bf16_f32 v62, v183, v185
	v_cvt_pk_bf16_f32 v63, v163, v184
	v_cvt_pk_bf16_f32 v64, v161, v182
	v_cvt_pk_bf16_f32 v65, v160, v162
	v_cvt_pk_bf16_f32 v66, v0, v1
	v_cvt_pk_bf16_f32 v67, v2, v3
	v_cvt_pk_bf16_f32 v68, v4, v5
	v_cvt_pk_bf16_f32 v69, v6, v7
	v_cvt_pk_bf16_f32 v70, v70, v71
	v_cvt_pk_bf16_f32 v71, v72, v73
	v_cvt_pk_bf16_f32 v72, v74, v75
	v_cvt_pk_bf16_f32 v73, v76, v77
	s_nop 1
	v_permlane32_swap_b32_e32 v13, v180
	v_permlane32_swap_b32_e32 v8, v10
	v_permlane32_swap_b32_e32 v9, v11
	v_permlane32_swap_b32_e32 v62, v64
	v_permlane32_swap_b32_e32 v63, v65
	v_permlane32_swap_b32_e32 v66, v68
	v_permlane32_swap_b32_e32 v67, v69
	v_permlane32_swap_b32_e32 v70, v72
	v_permlane32_swap_b32_e32 v71, v73
	v_lshl_add_u64 v[160:161], s[10:11], 0, v[158:159]
	v_add_co_u32_e32 v0, vcc, 0x2cc48000, v160
	s_nop 1
	v_addc_co_u32_e32 v1, vcc, 0, v161, vcc
	global_load_dwordx4 v[0:3], v[0:1], off
	s_and_saveexec_b64 s[0:1], s[42:43]
	s_cbranch_execz .LBB0_1153
	v_lshl_add_u64 v[4:5], s[10:11], 0, v[154:155]
	v_add_co_u32_e32 v4, vcc, 0x2cc48000, v4
	s_nop 1
	v_addc_co_u32_e32 v5, vcc, 0, v5, vcc
	global_load_dwordx4 v[138:141], v[4:5], off
; #define SBAR() __builtin_amdgcn_sched_barrier(0)
; template <int OFF> DEVFI s16x4 tr_read(int vb) { s16x4 r; asm volatile("ds_read_b64_tr_b16 %0, %1 offset:%2" : "=&v"(r) : "v"(vb), "i"(OFF) : "memory"); return r; }
; DEVFI void partialSM2(f32x16& p0, f32x16& p1, float& mhat, f32x16& negm, float& alpha, const float thr2, const bool first) {
;     float pmax = p0[0];
; #pragma unroll
;     for (int r = 1; r < 16; ++r) pmax = fmaxf(pmax, p0[r]);
; #pragma unroll
;     for (int r = 0; r < 16; ++r) pmax = fmaxf(pmax, p1[r]);
;     { auto rr = __builtin_amdgcn_permlane32_swap(__float_as_uint(pmax), __float_as_uint(pmax), false, false);
;       pmax = fmaxf(__uint_as_float(rr[0]), __uint_as_float(rr[1])); }
;     alpha = 1.f;
;     if (first || !__all(pmax <= thr2)) {
;         const float dl = first ? pmax : fmaxf(pmax, 0.f);
;         mhat += dl; alpha = first ? 1.f : __builtin_amdgcn_exp2f(-dl);
; #pragma unroll
;         for (int r = 0; r < 16; ++r) { p0[r] -= dl; p1[r] -= dl; }
; #pragma unroll
;         for (int r = 0; r < 16; ++r) negm[r] = -mhat;
;         asm volatile("" : "+v"(negm));
;     }
; template <int NCB, int D0> DEVFI void pv_one(f32x16& od, int vb, bf16x8 pa0, bf16x8 pa1, bf16x8 pa2, bf16x8 pa3) {
;     ...
;     const s16x4 l0 = tr_read<VOFF(0, 0)>(vb), h0 = tr_read<VOFF(0, 1)>(vb), l1 = tr_read<VOFF(1, 0)>(vb), h1 = tr_read<VOFF(1, 1)>(vb);
;     const s16x4 l2 = tr_read<VOFF(2, 0)>(vb), h2 = tr_read<VOFF(2, 1)>(vb), l3 = tr_read<VOFF(3, 0)>(vb), h3 = tr_read<VOFF(3, 1)>(vb);
;     ...
;     asm volatile("s_waitcnt lgkmcnt(0)" ::: "memory"); SBAR();
;     ...
;     od = __builtin_amdgcn_mfma_f32_32x32x16_bf16(pa0, PK(l0, h0), od, 0, 0, 0);
;     od = __builtin_amdgcn_mfma_f32_32x32x16_bf16(pa1, PK(l1, h1), od, 0, 0, 0);
;     od = __builtin_amdgcn_mfma_f32_32x32x16_bf16(pa2, PK(l2, h2), od, 0, 0, 0);
;     od = __builtin_amdgcn_mfma_f32_32x32x16_bf16(pa3, PK(l3, h3), od, 0, 0, 0);
;     ...
; }
.LBB0_1153:
	s_or_b64 exec, exec, s[0:1]
	v_lshl_add_u64 v[162:163], s[10:11], 0, v[156:157]
	v_add_co_u32_e32 v4, vcc, 0x2fc30000, v162
	s_nop 1
	v_addc_co_u32_e32 v5, vcc, 0, v163, vcc
	global_load_dwordx4 v[4:7], v[4:5], off
	ds_read_b64_tr_b16 v[74:75], v171 offset:0
	ds_read_b64_tr_b16 v[76:77], v171 offset:0x400
	ds_read_b64_tr_b16 v[182:183], v171 offset:0x800
	ds_read_b64_tr_b16 v[184:185], v171 offset:0xc00
	ds_read_b64_tr_b16 v[186:187], v171 offset:0x1000
	ds_read_b64_tr_b16 v[188:189], v171 offset:0x1400
	ds_read_b64_tr_b16 v[202:203], v171 offset:0x1800
	ds_read_b64_tr_b16 v[204:205], v171 offset:0x1c00
	s_waitcnt lgkmcnt(6)
	s_nop 0
	v_mfma_f32_32x32x16_bf16 v[30:45], v[8:11], v[74:77], v[30:45]
	ds_read_b64_tr_b16 v[74:75], v171 offset:0x200
	ds_read_b64_tr_b16 v[76:77], v171 offset:0x600
	s_waitcnt lgkmcnt(6)
	v_mfma_f32_32x32x16_bf16 v[30:45], v[62:65], v[182:185], v[30:45]
	ds_read_b64_tr_b16 v[182:183], v171 offset:0xa00
	ds_read_b64_tr_b16 v[184:185], v171 offset:0xe00
	s_waitcnt lgkmcnt(6)
	v_mfma_f32_32x32x16_bf16 v[30:45], v[66:69], v[186:189], v[30:45]
	ds_read_b64_tr_b16 v[186:187], v171 offset:0x1200
	ds_read_b64_tr_b16 v[188:189], v171 offset:0x1600
	s_waitcnt lgkmcnt(6)
	v_mfma_f32_32x32x16_bf16 v[30:45], v[70:73], v[202:205], v[30:45]
	ds_read_b64_tr_b16 v[202:203], v171 offset:0x1a00
	ds_read_b64_tr_b16 v[204:205], v171 offset:0x1e00
	s_waitcnt lgkmcnt(6)
	v_mfma_f32_32x32x16_bf16 v[14:29], v[8:11], v[74:77], v[14:29]
	v_max_f32_e32 v8, v94, v95
	v_max3_f32 v8, v8, v96, v97
	v_max3_f32 v8, v8, v98, v99
	v_max3_f32 v8, v8, v100, v101
	v_max3_f32 v8, v8, v102, v103
	s_waitcnt lgkmcnt(4)
	v_mfma_f32_32x32x16_bf16 v[14:29], v[62:65], v[182:185], v[14:29]
	v_max3_f32 v8, v8, v104, v105
	v_max3_f32 v8, v8, v106, v107
	v_max3_f32 v8, v8, v108, v109
	v_max3_f32 v8, v8, v78, v79
	v_max3_f32 v8, v8, v80, v81
	v_max3_f32 v8, v8, v82, v83
	v_max3_f32 v8, v8, v84, v85
	s_waitcnt lgkmcnt(2)
	v_mfma_f32_32x32x16_bf16 v[14:29], v[66:69], v[186:189], v[14:29]
	v_max3_f32 v8, v8, v86, v87
	v_max3_f32 v8, v8, v88, v89
	v_max3_f32 v8, v8, v90, v91
	v_max3_f32 v8, v8, v92, v93
	v_mov_b32_e32 v9, v8
	s_nop 1
	v_permlane32_swap_b32_e32 v8, v9
	s_waitcnt lgkmcnt(0)
	v_mfma_f32_32x32x16_bf16 v[14:29], v[70:73], v[202:205], v[14:29]
	v_max_f32_e32 v8, v8, v9
	v_cmp_ge_f32_e32 vcc, s33, v8
	s_cmp_eq_u64 vcc, exec
	v_mov_b32_e32 v181, 1.0
	s_cbranch_scc1 .LBB0_1155
	v_max_f32_e32 v8, v8, v8
	v_max_f32_e32 v8, 0, v8
	v_exp_f32_e64 v181, -v8
	v_add_f32_e32 v168, v168, v8
	v_xor_b32_e32 v46, 0x80000000, v168
	v_pk_add_f32 v[94:95], v[94:95], v[8:9] op_sel_hi:[1,0] neg_lo:[0,1] neg_hi:[0,1]
	v_pk_add_f32 v[96:97], v[96:97], v[8:9] op_sel_hi:[1,0] neg_lo:[0,1] neg_hi:[0,1]
	v_pk_add_f32 v[98:99], v[98:99], v[8:9] op_sel_hi:[1,0] neg_lo:[0,1] neg_hi:[0,1]
	v_pk_add_f32 v[100:101], v[100:101], v[8:9] op_sel_hi:[1,0] neg_lo:[0,1] neg_hi:[0,1]
	v_pk_add_f32 v[102:103], v[102:103], v[8:9] op_sel_hi:[1,0] neg_lo:[0,1] neg_hi:[0,1]
	v_pk_add_f32 v[104:105], v[104:105], v[8:9] op_sel_hi:[1,0] neg_lo:[0,1] neg_hi:[0,1]
	v_pk_add_f32 v[106:107], v[106:107], v[8:9] op_sel_hi:[1,0] neg_lo:[0,1] neg_hi:[0,1]
	v_pk_add_f32 v[108:109], v[108:109], v[8:9] op_sel_hi:[1,0] neg_lo:[0,1] neg_hi:[0,1]
	v_sub_f32_e32 v93, v93, v8
	v_sub_f32_e32 v92, v92, v8
	v_sub_f32_e32 v91, v91, v8
	v_sub_f32_e32 v90, v90, v8
	v_sub_f32_e32 v89, v89, v8
	v_sub_f32_e32 v88, v88, v8
	v_sub_f32_e32 v87, v87, v8
	v_sub_f32_e32 v86, v86, v8
	v_sub_f32_e32 v85, v85, v8
	v_sub_f32_e32 v84, v84, v8
	v_sub_f32_e32 v83, v83, v8
	v_sub_f32_e32 v82, v82, v8
	v_sub_f32_e32 v81, v81, v8
	v_sub_f32_e32 v80, v80, v8
	v_sub_f32_e32 v79, v79, v8
	v_sub_f32_e32 v78, v78, v8
	v_mov_b32_e32 v47, v46
	v_mov_b32_e32 v48, v46
	v_mov_b32_e32 v49, v46
	v_mov_b32_e32 v50, v46
	v_mov_b32_e32 v51, v46
	v_mov_b32_e32 v52, v46
	v_mov_b32_e32 v53, v46
	v_mov_b32_e32 v54, v46
	v_mov_b32_e32 v55, v46
	v_mov_b32_e32 v56, v46
	v_mov_b32_e32 v57, v46
	v_mov_b32_e32 v58, v46
	v_mov_b32_e32 v59, v46
	v_mov_b32_e32 v60, v46
	v_mov_b32_e32 v61, v46

; #define SBAR() __builtin_amdgcn_sched_barrier(0)
; #define QKT(P0, P1, KP) do { if constexpr (PRE) qkt<ND0>(P0, P1, KP, qr, r32, hi, negm); else qkt<ND0>(P0, P1, KP, qr, r32, hi); } while (0)
; DEVFI void finishSM(f32x16& p0, f32x16& p1, float alpha, float& l_reg, bf16x8& pa0, bf16x8& pa1, bf16x8& pa2, bf16x8& pa3) {
; #pragma unroll
;     for (int r = 0; r < 16; ++r) p1[r] = __builtin_amdgcn_exp2f(p1[r]);
;     float ps = 0;
; #pragma unroll
;     for (int r = 0; r < 16; ++r) ps += p0[r];
; #pragma unroll
;     for (int r = 0; r < 16; ++r) ps += p1[r];
;     { auto rr = __builtin_amdgcn_permlane32_swap(__float_as_uint(ps), __float_as_uint(ps), false, false);
;       ps = __uint_as_float(rr[0]) + __uint_as_float(rr[1]); }
;     l_reg = l_reg * alpha + ps;
;     ...
;     PK4(p0, 0, pa0); PK4(p0, 8, pa1); PK4(p1, 0, pa2); PK4(p1, 8, pa3);
; template <int DQK, int DV, bool PRE = false>
; DEVFI void attn_unit(const bf16_t* __restrict__ Qb, int ldq, const bf16_t* __restrict__ Kh, int ldk, const bf16_t* __restrict__ Vh, int ldv,
;                      bf16_t* __restrict__ Ob, int ldo, int seq, float scale, char* lds) {
;     ...
;         SBAR(); QKT(pA0, pA1, K_lds);
;         finishSM(pB0, pB1, alB, l_reg, pa0, pa1, pa2, pa3); SBAR();
;         if (j + 3 < NT) SLOAD(0, (j + 3) * KVBLK); SBAR();
.LBB0_1161:
	v_exp_f32_e32 v8, v94
	v_exp_f32_e32 v9, v96
	v_exp_f32_e32 v10, v98
	v_exp_f32_e32 v11, v100
	v_exp_f32_e32 v205, v95
	v_exp_f32_e32 v204, v97
	v_exp_f32_e32 v203, v99
	v_exp_f32_e32 v202, v101
	v_exp_f32_e32 v187, v102
	v_exp_f32_e32 v189, v103
	v_exp_f32_e32 v185, v104
	v_exp_f32_e32 v188, v105
	v_exp_f32_e32 v183, v106
	v_exp_f32_e32 v186, v107
	v_exp_f32_e32 v182, v108
	v_exp_f32_e32 v184, v109
	s_waitcnt lgkmcnt(0)
	s_barrier
	ds_read_b128 v[62:65], v177 offset:16384
	ds_read_b128 v[206:209], v177 offset:24576
	v_exp_f32_e32 v190, v78
	v_add_f32_e32 v78, v8, v205
	s_waitcnt lgkmcnt(1)
	v_mfma_f32_32x32x16_bf16 v[94:109], v[62:65], v[130:133], v[46:61]
	v_add_f32_e32 v78, v9, v78
	v_add_f32_e32 v78, v204, v78
	v_add_f32_e32 v78, v10, v78
	v_add_f32_e32 v78, v203, v78
	v_add_f32_e32 v78, v11, v78
	v_add_f32_e32 v78, v202, v78
	v_add_f32_e32 v78, v187, v78
	s_waitcnt lgkmcnt(0)
	v_mfma_f32_32x32x16_bf16 v[62:77], v[206:209], v[130:133], v[46:61]
	ds_read_b128 v[206:209], v178 offset:16384
	ds_read_b128 v[210:213], v178 offset:24576
	v_add_f32_e32 v78, v189, v78
	v_add_f32_e32 v78, v185, v78
	v_add_f32_e32 v78, v188, v78
	v_add_f32_e32 v78, v183, v78
	v_exp_f32_e32 v191, v79
	v_add_f32_e32 v78, v186, v78
	s_waitcnt lgkmcnt(1)
	v_mfma_f32_32x32x16_bf16 v[94:109], v[206:209], v[126:129], v[94:109]
	v_add_f32_e32 v78, v182, v78
	v_add_f32_e32 v78, v184, v78
	v_add_f32_e32 v78, v190, v78
	v_add_f32_e32 v78, v191, v78
	v_exp_f32_e32 v85, v85
	v_exp_f32_e32 v86, v86
	v_exp_f32_e32 v87, v87
	s_waitcnt lgkmcnt(0)
	v_mfma_f32_32x32x16_bf16 v[62:77], v[210:213], v[126:129], v[62:77]
	ds_read_b128 v[206:209], v176 offset:16384
	ds_read_b128 v[210:213], v176 offset:24576
	v_exp_f32_e32 v88, v88
	v_exp_f32_e32 v89, v89
	v_exp_f32_e32 v92, v92
	v_exp_f32_e32 v93, v93
	s_waitcnt lgkmcnt(1)
	v_mfma_f32_32x32x16_bf16 v[94:109], v[206:209], v[122:125], v[94:109]
	s_waitcnt lgkmcnt(0)
	v_mfma_f32_32x32x16_bf16 v[62:77], v[210:213], v[122:125], v[62:77]
	ds_read_b128 v[206:209], v175 offset:16384
	ds_read_b128 v[210:213], v175 offset:24576
	s_waitcnt lgkmcnt(1)
	v_mfma_f32_32x32x16_bf16 v[94:109], v[206:209], v[118:121], v[94:109]
	s_waitcnt lgkmcnt(0)
	v_mfma_f32_32x32x16_bf16 v[62:77], v[210:213], v[118:121], v[62:77]
	ds_read_b128 v[206:209], v174 offset:16384
	ds_read_b128 v[210:213], v174 offset:24576
	s_waitcnt lgkmcnt(1)
	v_mfma_f32_32x32x16_bf16 v[94:109], v[206:209], v[114:117], v[94:109]
	s_waitcnt lgkmcnt(0)
	v_mfma_f32_32x32x16_bf16 v[62:77], v[210:213], v[114:117], v[62:77]
	ds_read_b128 v[206:209], v172 offset:16384
	ds_read_b128 v[210:213], v172 offset:24576
	v_cvt_pk_bf16_f32 v8, v8, v205
	v_cvt_pk_bf16_f32 v9, v9, v204
	v_cvt_pk_bf16_f32 v10, v10, v203
	v_cvt_pk_bf16_f32 v11, v11, v202
	s_nop 0
	v_permlane32_swap_b32_e32 v8, v10
	s_waitcnt lgkmcnt(1)
	v_mfma_f32_32x32x16_bf16 v[94:109], v[206:209], v[110:113], v[94:109]
	v_exp_f32_e32 v206, v80
	v_exp_f32_e32 v207, v81
	v_exp_f32_e32 v208, v82
	v_exp_f32_e32 v209, v83
	v_add_f32_e32 v78, v206, v78
	v_add_f32_e32 v78, v207, v78
	v_add_f32_e32 v78, v208, v78
	s_waitcnt lgkmcnt(0)
	v_mfma_f32_32x32x16_bf16 v[62:77], v[210:213], v[110:113], v[62:77]
	v_exp_f32_e32 v210, v84
	v_add_f32_e32 v78, v209, v78
	v_exp_f32_e32 v211, v90
	v_exp_f32_e32 v212, v91
	v_add_f32_e32 v78, v210, v78
	v_add_f32_e32 v78, v85, v78
	v_add_f32_e32 v78, v86, v78
	v_add_f32_e32 v78, v87, v78
	v_add_f32_e32 v78, v88, v78
	v_add_f32_e32 v78, v89, v78
	v_add_f32_e32 v78, v211, v78
	v_add_f32_e32 v78, v212, v78
	v_add_f32_e32 v78, v92, v78
	v_add_f32_e32 v90, v93, v78
	v_mov_b32_e32 v91, v90
	v_cvt_pk_bf16_f32 v78, v187, v189
	v_cvt_pk_bf16_f32 v79, v185, v188
	v_cvt_pk_bf16_f32 v80, v183, v186
	v_cvt_pk_bf16_f32 v81, v182, v184
	v_cvt_pk_bf16_f32 v82, v190, v191
	v_cvt_pk_bf16_f32 v83, v206, v207
	v_cvt_pk_bf16_f32 v84, v208, v209
	v_cvt_pk_bf16_f32 v85, v210, v85
	v_cvt_pk_bf16_f32 v86, v86, v87
	v_cvt_pk_bf16_f32 v87, v88, v89
	v_cvt_pk_bf16_f32 v88, v211, v212
	v_cvt_pk_bf16_f32 v89, v92, v93
	s_nop 1
	v_permlane32_swap_b32_e32 v90, v91
	v_permlane32_swap_b32_e32 v9, v11
	v_permlane32_swap_b32_e32 v78, v80
	v_permlane32_swap_b32_e32 v79, v81
	v_permlane32_swap_b32_e32 v82, v84
	v_permlane32_swap_b32_e32 v83, v85
	v_permlane32_swap_b32_e32 v86, v88
	v_permlane32_swap_b32_e32 v87, v89
	s_cmp_ge_u32 s18, s59
	s_cselect_b64 s[0:1], -1, 0
	s_and_b64 vcc, exec, s[0:1]
	s_cbranch_vccnz .LBB0_1165
	v_add_co_u32_e32 v92, vcc, 0x2cc60000, v160
	s_nop 1
	v_addc_co_u32_e32 v93, vcc, 0, v161, vcc
	global_load_dwordx4 v[142:145], v[92:93], off
	s_and_saveexec_b64 s[16:17], s[42:43]
	s_cbranch_execz .LBB0_1164
	v_lshl_add_u64 v[92:93], s[10:11], 0, v[154:155]
	v_add_co_u32_e32 v92, vcc, 0x2cc60000, v92
	s_nop 1
	v_addc_co_u32_e32 v93, vcc, 0, v93, vcc
	global_load_dwordx4 v[134:137], v[92:93], off

; #define SBAR() __builtin_amdgcn_sched_barrier(0)
; template <int OFF> DEVFI s16x4 tr_read(int vb) { s16x4 r; asm volatile("ds_read_b64_tr_b16 %0, %1 offset:%2" : "=&v"(r) : "v"(vb), "i"(OFF) : "memory"); return r; }
; DEVFI void partialSM2(f32x16& p0, f32x16& p1, float& mhat, f32x16& negm, float& alpha, const float thr2, const bool first) {
;     float pmax = p0[0];
; #pragma unroll
;     for (int r = 1; r < 16; ++r) pmax = fmaxf(pmax, p0[r]);
; #pragma unroll
;     for (int r = 0; r < 16; ++r) pmax = fmaxf(pmax, p1[r]);
;     { auto rr = __builtin_amdgcn_permlane32_swap(__float_as_uint(pmax), __float_as_uint(pmax), false, false);
;       pmax = fmaxf(__uint_as_float(rr[0]), __uint_as_float(rr[1])); }
;     alpha = 1.f;
;     if (first || !__all(pmax <= thr2)) {
;         const float dl = first ? pmax : fmaxf(pmax, 0.f);
;         mhat += dl; alpha = first ? 1.f : __builtin_amdgcn_exp2f(-dl);
; #pragma unroll
;         for (int r = 0; r < 16; ++r) { p0[r] -= dl; p1[r] -= dl; }
; #pragma unroll
;         for (int r = 0; r < 16; ++r) negm[r] = -mhat;
;         asm volatile("" : "+v"(negm));
;     }
; template <int NCB, int D0> DEVFI void pv_one(f32x16& od, int vb, bf16x8 pa0, bf16x8 pa1, bf16x8 pa2, bf16x8 pa3) {
;     ...
;     const s16x4 l0 = tr_read<VOFF(0, 0)>(vb), h0 = tr_read<VOFF(0, 1)>(vb), l1 = tr_read<VOFF(1, 0)>(vb), h1 = tr_read<VOFF(1, 1)>(vb);
;     const s16x4 l2 = tr_read<VOFF(2, 0)>(vb), h2 = tr_read<VOFF(2, 1)>(vb), l3 = tr_read<VOFF(3, 0)>(vb), h3 = tr_read<VOFF(3, 1)>(vb);
;     ...
;     asm volatile("s_waitcnt lgkmcnt(0)" ::: "memory"); SBAR();
;     ...
;     od = __builtin_amdgcn_mfma_f32_32x32x16_bf16(pa0, PK(l0, h0), od, 0, 0, 0);
;     od = __builtin_amdgcn_mfma_f32_32x32x16_bf16(pa1, PK(l1, h1), od, 0, 0, 0);
;     od = __builtin_amdgcn_mfma_f32_32x32x16_bf16(pa2, PK(l2, h2), od, 0, 0, 0);
;     od = __builtin_amdgcn_mfma_f32_32x32x16_bf16(pa3, PK(l3, h3), od, 0, 0, 0);
;     ...
; }
.LBB0_1165:
	ds_read_b64_tr_b16 v[160:161], v167 offset:0
	ds_read_b64_tr_b16 v[162:163], v167 offset:0x400
	ds_read_b64_tr_b16 v[182:183], v167 offset:0x800
	ds_read_b64_tr_b16 v[184:185], v167 offset:0xc00
	ds_read_b64_tr_b16 v[186:187], v167 offset:0x1000
	ds_read_b64_tr_b16 v[188:189], v167 offset:0x1400
	ds_read_b64_tr_b16 v[202:203], v167 offset:0x1800
	ds_read_b64_tr_b16 v[204:205], v167 offset:0x1c00
	s_waitcnt lgkmcnt(6)
	s_nop 0
	v_mfma_f32_32x32x16_bf16 v[30:45], v[8:11], v[160:163], v[30:45]
	ds_read_b64_tr_b16 v[160:161], v167 offset:0x200
	ds_read_b64_tr_b16 v[162:163], v167 offset:0x600
	s_waitcnt lgkmcnt(6)
	v_mfma_f32_32x32x16_bf16 v[30:45], v[78:81], v[182:185], v[30:45]
	ds_read_b64_tr_b16 v[182:183], v167 offset:0xa00
	ds_read_b64_tr_b16 v[184:185], v167 offset:0xe00
	s_waitcnt lgkmcnt(6)
	v_mfma_f32_32x32x16_bf16 v[30:45], v[82:85], v[186:189], v[30:45]
	ds_read_b64_tr_b16 v[186:187], v167 offset:0x1200
	ds_read_b64_tr_b16 v[188:189], v167 offset:0x1600
	s_waitcnt lgkmcnt(6)
	v_mfma_f32_32x32x16_bf16 v[30:45], v[86:89], v[202:205], v[30:45]
	ds_read_b64_tr_b16 v[202:203], v167 offset:0x1a00
	ds_read_b64_tr_b16 v[204:205], v167 offset:0x1e00
	s_waitcnt lgkmcnt(6)
	v_mfma_f32_32x32x16_bf16 v[14:29], v[8:11], v[160:163], v[14:29]
	v_max_f32_e32 v8, v94, v95
	v_max3_f32 v8, v8, v96, v97
	v_max3_f32 v8, v8, v98, v99
	v_max3_f32 v8, v8, v100, v101
	v_max3_f32 v8, v8, v102, v103
	s_waitcnt lgkmcnt(4)
	v_mfma_f32_32x32x16_bf16 v[14:29], v[78:81], v[182:185], v[14:29]
	v_max3_f32 v8, v8, v104, v105
	v_max3_f32 v8, v8, v106, v107
	v_max3_f32 v8, v8, v108, v109
	v_max3_f32 v8, v8, v62, v63
	v_max3_f32 v8, v8, v64, v65
	v_max3_f32 v8, v8, v66, v67
	v_max3_f32 v8, v8, v68, v69
	s_waitcnt lgkmcnt(2)
	v_mfma_f32_32x32x16_bf16 v[14:29], v[82:85], v[186:189], v[14:29]
	v_max3_f32 v8, v8, v70, v71
	v_max3_f32 v8, v8, v72, v73
	v_max3_f32 v8, v8, v74, v75
	v_max3_f32 v8, v8, v76, v77
	v_mov_b32_e32 v9, v8
	s_nop 1
	v_permlane32_swap_b32_e32 v8, v9
	s_waitcnt lgkmcnt(0)
	v_mfma_f32_32x32x16_bf16 v[14:29], v[86:89], v[202:205], v[14:29]
	v_max_f32_e32 v9, v8, v9
	v_cmp_ge_f32_e32 vcc, s33, v9
	s_cmp_eq_u64 vcc, exec
	v_mov_b32_e32 v8, 1.0
	s_cbranch_scc1 .LBB0_1167
	v_max_f32_e32 v8, v9, v9
	v_max_f32_e32 v10, 0, v8
	v_exp_f32_e64 v8, -v10
	v_add_f32_e32 v168, v168, v10
	v_xor_b32_e32 v46, 0x80000000, v168
	v_pk_add_f32 v[94:95], v[94:95], v[10:11] op_sel_hi:[1,0] neg_lo:[0,1] neg_hi:[0,1]
	v_pk_add_f32 v[96:97], v[96:97], v[10:11] op_sel_hi:[1,0] neg_lo:[0,1] neg_hi:[0,1]
	v_pk_add_f32 v[98:99], v[98:99], v[10:11] op_sel_hi:[1,0] neg_lo:[0,1] neg_hi:[0,1]
	v_pk_add_f32 v[100:101], v[100:101], v[10:11] op_sel_hi:[1,0] neg_lo:[0,1] neg_hi:[0,1]
	v_pk_add_f32 v[102:103], v[102:103], v[10:11] op_sel_hi:[1,0] neg_lo:[0,1] neg_hi:[0,1]
	v_pk_add_f32 v[104:105], v[104:105], v[10:11] op_sel_hi:[1,0] neg_lo:[0,1] neg_hi:[0,1]
	v_pk_add_f32 v[106:107], v[106:107], v[10:11] op_sel_hi:[1,0] neg_lo:[0,1] neg_hi:[0,1]
	v_pk_add_f32 v[108:109], v[108:109], v[10:11] op_sel_hi:[1,0] neg_lo:[0,1] neg_hi:[0,1]
	v_sub_f32_e32 v77, v77, v10
	v_sub_f32_e32 v76, v76, v10
	v_sub_f32_e32 v75, v75, v10
	v_sub_f32_e32 v74, v74, v10
	v_sub_f32_e32 v73, v73, v10
	v_sub_f32_e32 v72, v72, v10
	v_sub_f32_e32 v71, v71, v10
	v_sub_f32_e32 v70, v70, v10
	v_sub_f32_e32 v69, v69, v10
	v_sub_f32_e32 v68, v68, v10
	v_sub_f32_e32 v67, v67, v10
	v_sub_f32_e32 v66, v66, v10
	v_sub_f32_e32 v65, v65, v10
	v_sub_f32_e32 v64, v64, v10
	v_sub_f32_e32 v63, v63, v10
	v_sub_f32_e32 v62, v62, v10
	v_mov_b32_e32 v47, v46
	v_mov_b32_e32 v48, v46
	v_mov_b32_e32 v49, v46
	v_mov_b32_e32 v50, v46
	v_mov_b32_e32 v51, v46
	v_mov_b32_e32 v52, v46
	v_mov_b32_e32 v53, v46
	v_mov_b32_e32 v54, v46
	v_mov_b32_e32 v55, v46
	v_mov_b32_e32 v56, v46
	v_mov_b32_e32 v57, v46
	v_mov_b32_e32 v58, v46
	v_mov_b32_e32 v59, v46
	v_mov_b32_e32 v60, v46
	v_mov_b32_e32 v61, v46
